# saddr LDS-DMA addressing in GEMM loops up, glu, a_out, down
# baseline (speedup 1.0000x reference)
; #define PG8_STAGE(bufoff, gbase, voff) do { _Pragma("unroll") for (int _i = 0; _i < 2; ++_i) \
;         __builtin_amdgcn_global_load_lds((const unsigned*)((const char*)(gbase) + (voff)[_i]), (PG8_LAS unsigned*)(lds + (bufoff) + ldsw + _i * 8192), 16, 0, 0); } while (0)
; #define PG8_LDA(dst, b, h) do { _Pragma("unroll") for (int m = 0; m < 4; ++m) _Pragma("unroll") for (int k = 0; k < 2; ++k) dst[m][k] = *(const PG8_LAS bf16x8*)(lds + PG8_SA(b, h) + aoff + m * 2048 + k * 1024); } while (0)
; #define PG8_LDB(dst, b, h) do { _Pragma("unroll") for (int n = 0; n < 2; ++n) _Pragma("unroll") for (int k = 0; k < 2; ++k) dst[n][k] = *(const PG8_LAS bf16x8*)(lds + PG8_SB(b, h) + boff + n * 2048 + k * 1024); } while (0)
; #define PG8_MMA(ai, bj, At, Bt) do { __builtin_amdgcn_s_setprio(3); _Pragma("unroll") for (int m = 0; m < 4; ++m) _Pragma("unroll") for (int n = 0; n < 2; ++n) _Pragma("unroll") for (int k = 0; k < 2; ++k) \
;         acc[ai][bj][m][n] = __builtin_amdgcn_mfma_f32_16x16x32_bf16(Bt[n][k], At[m][k], acc[ai][bj][m][n], 0, 0, 0); __builtin_amdgcn_s_setprio(0); } while (0)
; #define PG8_WAIT_V(n) asm volatile("s_waitcnt vmcnt(" #n ")" ::: "memory")
; #define PG8_WAIT_L(n) asm volatile("s_waitcnt lgkmcnt(" #n ")" ::: "memory")
; #define PG8_BAR __builtin_amdgcn_s_barrier()
; #define PG8_SCHED __builtin_amdgcn_sched_barrier(0)
; template <class Epi, class Sched, bool ALIGN_EPI = false, bool SP2 = false>
; __device__ __forceinline__ void gemm_phase(PG8_LAS unsigned char* lds, const Gemm g, const Sched& S, const Epi& E, const int tid_in) {
;     ...
;             PG8_LDB(B0, 0, 0); PG8_LDB(B1, 0, 1); PG8_SCHED; PG8_LDA(At, 0, 0); PG8_STAGE(PG8_SA(1, 1), a1 + hstepA, voffA);
;             PG8_WAIT_V(8); PG8_WAIT_L(0); PG8_BAR; PG8_MMA(0, 0, At, B0); PG8_MMA(0, 1, At, B1); PG8_BAR; PG8_SCHED;
;             PG8_LDA(At, 0, 1); PG8_STAGE(PG8_SB(0, 0), b2, voffB); PG8_STAGE(PG8_SB(0, 1), b2 + hstep, voffB); PG8_STAGE(PG8_SA(0, 0), a2, voffA);
;             PG8_WAIT_V(8); PG8_WAIT_L(0); PG8_BAR; PG8_MMA(1, 0, At, B0); PG8_MMA(1, 1, At, B1); PG8_BAR; PG8_SCHED;
.LBB0_107:
	s_add_u32 s22, s26, 0xfff80080
	s_addc_u32 s23, s27, -1
	s_add_i32 s40, 0, 0x10000
	s_cmp_eq_u32 s81, 28
	s_cselect_b32 s59, s43, s23
	s_cselect_b32 s58, s47, s22
	s_cselect_b32 s23, s45, s61
	s_cselect_b32 s22, vcc_lo, vcc_hi
	s_add_i32 s46, 0, 0x14000
	v_add_u32_e32 v142, s40, v191
	v_add_u32_e32 v168, s46, v191
	ds_read_b128 v[114:117], v142
	ds_read_b128 v[134:137], v142 offset:1024
	ds_read_b128 v[138:141], v142 offset:2048
	ds_read_b128 v[142:145], v142 offset:3072
	ds_read_b128 v[146:149], v168
	ds_read_b128 v[150:153], v168 offset:1024
	ds_read_b128 v[154:157], v168 offset:2048
	ds_read_b128 v[168:171], v168 offset:3072
	s_add_i32 m0, s71, 0xc000
	ds_read_b128 v[172:175], v193
	ds_read_b128 v[176:179], v193 offset:1024
	ds_read_b128 v[180:183], v193 offset:2048
	ds_read_b128 v[184:187], v193 offset:3072
	ds_read_b128 v[194:197], v193 offset:4096
	ds_read_b128 v[206:209], v193 offset:5120
	ds_read_b128 v[210:213], v193 offset:6144
	ds_read_b128 v[214:217], v193 offset:7168
	global_load_lds_dwordx4 v164, s[26:27]
	s_add_i32 m0, s71, 0xe000
	s_nop 0
	global_load_lds_dwordx4 v166, s[26:27]
	s_waitcnt vmcnt(8)
	s_waitcnt lgkmcnt(0)
	s_barrier
	s_setprio 3
	s_waitcnt lgkmcnt(0)
	v_mfma_f32_16x16x32_bf16 v[126:129], v[114:117], v[172:175], v[126:129]
	v_mfma_f32_16x16x32_bf16 v[122:125], v[138:141], v[172:175], v[122:125]
	v_mfma_f32_16x16x32_bf16 v[110:113], v[114:117], v[180:183], v[110:113]
	v_mfma_f32_16x16x32_bf16 v[102:105], v[138:141], v[180:183], v[102:105]
	v_mfma_f32_16x16x32_bf16 v[94:97], v[114:117], v[194:197], v[94:97]
	v_mfma_f32_16x16x32_bf16 v[86:89], v[138:141], v[194:197], v[86:89]
	v_mfma_f32_16x16x32_bf16 v[78:81], v[114:117], v[210:213], v[78:81]
	v_mfma_f32_16x16x32_bf16 v[70:73], v[138:141], v[210:213], v[70:73]
	v_mfma_f32_16x16x32_bf16 v[126:129], v[134:137], v[176:179], v[126:129]
	v_mfma_f32_16x16x32_bf16 v[122:125], v[142:145], v[176:179], v[122:125]
	v_mfma_f32_16x16x32_bf16 v[110:113], v[134:137], v[184:187], v[110:113]
	v_mfma_f32_16x16x32_bf16 v[102:105], v[142:145], v[184:187], v[102:105]
	v_mfma_f32_16x16x32_bf16 v[94:97], v[134:137], v[206:209], v[94:97]
	v_mfma_f32_16x16x32_bf16 v[86:89], v[142:145], v[206:209], v[86:89]
	v_mfma_f32_16x16x32_bf16 v[78:81], v[134:137], v[214:217], v[78:81]
	v_mfma_f32_16x16x32_bf16 v[70:73], v[142:145], v[214:217], v[70:73]
	s_setprio 0
	s_setprio 3
	v_mfma_f32_16x16x32_bf16 v[130:133], v[146:149], v[172:175], v[130:133]
	v_mfma_f32_16x16x32_bf16 v[118:121], v[154:157], v[172:175], v[118:121]
	v_mfma_f32_16x16x32_bf16 v[106:109], v[146:149], v[180:183], v[106:109]
	v_mfma_f32_16x16x32_bf16 v[98:101], v[154:157], v[180:183], v[98:101]
	v_mfma_f32_16x16x32_bf16 v[90:93], v[146:149], v[194:197], v[90:93]
	v_mfma_f32_16x16x32_bf16 v[82:85], v[154:157], v[194:197], v[82:85]
	v_mfma_f32_16x16x32_bf16 v[74:77], v[146:149], v[210:213], v[74:77]
	v_mfma_f32_16x16x32_bf16 v[66:69], v[154:157], v[210:213], v[66:69]
	v_mfma_f32_16x16x32_bf16 v[130:133], v[150:153], v[176:179], v[130:133]
	v_mfma_f32_16x16x32_bf16 v[118:121], v[168:171], v[176:179], v[118:121]
	v_mfma_f32_16x16x32_bf16 v[106:109], v[150:153], v[184:187], v[106:109]
	v_mfma_f32_16x16x32_bf16 v[98:101], v[168:171], v[184:187], v[98:101]
	v_mfma_f32_16x16x32_bf16 v[90:93], v[150:153], v[206:209], v[90:93]
	v_mfma_f32_16x16x32_bf16 v[82:85], v[168:171], v[206:209], v[82:85]
	v_mfma_f32_16x16x32_bf16 v[74:77], v[150:153], v[214:217], v[74:77]
	v_mfma_f32_16x16x32_bf16 v[66:69], v[168:171], v[214:217], v[66:69]
	s_setprio 0
	s_barrier
	s_add_i32 s40, s40, s70
	s_mov_b32 m0, s40
	ds_read_b128 v[172:175], v193 offset:16384
	ds_read_b128 v[176:179], v193 offset:17408
	ds_read_b128 v[180:183], v193 offset:18432
	ds_read_b128 v[184:187], v193 offset:19456
	ds_read_b128 v[194:197], v193 offset:20480
	ds_read_b128 v[206:209], v193 offset:21504
	ds_read_b128 v[210:213], v193 offset:22528
	ds_read_b128 v[214:217], v193 offset:23552
	global_load_lds_dwordx4 v64, s[22:23]
	s_add_i32 m0, s40, 0x2000
	s_add_u32 s40, s22, 0x80000
	s_addc_u32 s41, s23, 0
	s_add_i32 s46, s46, s70
	global_load_lds_dwordx4 v158, s[22:23]
	s_mov_b32 m0, s46
	global_load_lds_dwordx4 v64, s[40:41]
	s_add_i32 m0, s46, 0x2000
	s_nop 0
	global_load_lds_dwordx4 v158, s[40:41]
	s_mov_b32 m0, s71
	s_nop 0
	global_load_lds_dwordx4 v162, s[58:59]
	s_mov_b32 m0, s72
	s_nop 0
	global_load_lds_dwordx4 v160, s[58:59]
	s_waitcnt vmcnt(8)
	s_waitcnt lgkmcnt(0)
	s_barrier
	s_setprio 3
	s_waitcnt lgkmcnt(0)
	v_mfma_f32_16x16x32_bf16 v[60:63], v[114:117], v[172:175], v[60:63]
	v_mfma_f32_16x16x32_bf16 v[52:55], v[138:141], v[172:175], v[52:55]
	v_mfma_f32_16x16x32_bf16 v[44:47], v[114:117], v[180:183], v[44:47]
	v_mfma_f32_16x16x32_bf16 v[36:39], v[138:141], v[180:183], v[36:39]
	v_mfma_f32_16x16x32_bf16 v[28:31], v[114:117], v[194:197], v[28:31]
	v_mfma_f32_16x16x32_bf16 v[20:23], v[138:141], v[194:197], v[20:23]
	v_mfma_f32_16x16x32_bf16 v[12:15], v[114:117], v[210:213], v[12:15]
	v_mfma_f32_16x16x32_bf16 v[4:7], v[138:141], v[210:213], v[4:7]
	v_mfma_f32_16x16x32_bf16 v[60:63], v[134:137], v[176:179], v[60:63]
	v_mfma_f32_16x16x32_bf16 v[52:55], v[142:145], v[176:179], v[52:55]
	v_mfma_f32_16x16x32_bf16 v[44:47], v[134:137], v[184:187], v[44:47]
	v_mfma_f32_16x16x32_bf16 v[36:39], v[142:145], v[184:187], v[36:39]
	v_mfma_f32_16x16x32_bf16 v[28:31], v[134:137], v[206:209], v[28:31]
	v_mfma_f32_16x16x32_bf16 v[20:23], v[142:145], v[206:209], v[20:23]
	v_mfma_f32_16x16x32_bf16 v[12:15], v[134:137], v[214:217], v[12:15]
	v_mfma_f32_16x16x32_bf16 v[4:7], v[142:145], v[214:217], v[4:7]
	s_setprio 0
	s_setprio 3
	v_mfma_f32_16x16x32_bf16 v[56:59], v[146:149], v[172:175], v[56:59]
	v_mfma_f32_16x16x32_bf16 v[48:51], v[154:157], v[172:175], v[48:51]
	v_mfma_f32_16x16x32_bf16 v[40:43], v[146:149], v[180:183], v[40:43]
	v_mfma_f32_16x16x32_bf16 v[32:35], v[154:157], v[180:183], v[32:35]
	v_mfma_f32_16x16x32_bf16 v[24:27], v[146:149], v[194:197], v[24:27]
	v_mfma_f32_16x16x32_bf16 v[16:19], v[154:157], v[194:197], v[16:19]
	v_mfma_f32_16x16x32_bf16 v[8:11], v[146:149], v[210:213], v[8:11]
	v_mfma_f32_16x16x32_bf16 v[0:3], v[154:157], v[210:213], v[0:3]
	v_mfma_f32_16x16x32_bf16 v[56:59], v[150:153], v[176:179], v[56:59]
	v_mfma_f32_16x16x32_bf16 v[48:51], v[168:171], v[176:179], v[48:51]
	v_mfma_f32_16x16x32_bf16 v[40:43], v[150:153], v[184:187], v[40:43]
	v_mfma_f32_16x16x32_bf16 v[32:35], v[168:171], v[184:187], v[32:35]
	v_mfma_f32_16x16x32_bf16 v[24:27], v[150:153], v[206:209], v[24:27]
	v_mfma_f32_16x16x32_bf16 v[16:19], v[168:171], v[206:209], v[16:19]
	v_mfma_f32_16x16x32_bf16 v[8:11], v[150:153], v[214:217], v[8:11]
	v_mfma_f32_16x16x32_bf16 v[0:3], v[168:171], v[214:217], v[0:3]
	s_setprio 0
	s_barrier
; #define PG8_STAGE(bufoff, gbase, voff) do { _Pragma("unroll") for (int _i = 0; _i < 2; ++_i) \
;         __builtin_amdgcn_global_load_lds((const unsigned*)((const char*)(gbase) + (voff)[_i]), (PG8_LAS unsigned*)(lds + (bufoff) + ldsw + _i * 8192), 16, 0, 0); } while (0)
; #define PG8_LDA(dst, b, h) do { _Pragma("unroll") for (int m = 0; m < 4; ++m) _Pragma("unroll") for (int k = 0; k < 2; ++k) dst[m][k] = *(const PG8_LAS bf16x8*)(lds + PG8_SA(b, h) + aoff + m * 2048 + k * 1024); } while (0)
; #define PG8_LDB(dst, b, h) do { _Pragma("unroll") for (int n = 0; n < 2; ++n) _Pragma("unroll") for (int k = 0; k < 2; ++k) dst[n][k] = *(const PG8_LAS bf16x8*)(lds + PG8_SB(b, h) + boff + n * 2048 + k * 1024); } while (0)
; #define PG8_MMA(ai, bj, At, Bt) do { __builtin_amdgcn_s_setprio(3); _Pragma("unroll") for (int m = 0; m < 4; ++m) _Pragma("unroll") for (int n = 0; n < 2; ++n) _Pragma("unroll") for (int k = 0; k < 2; ++k) \
;         acc[ai][bj][m][n] = __builtin_amdgcn_mfma_f32_16x16x32_bf16(Bt[n][k], At[m][k], acc[ai][bj][m][n], 0, 0, 0); __builtin_amdgcn_s_setprio(0); } while (0)
; #define PG8_WAIT_V(n) asm volatile("s_waitcnt vmcnt(" #n ")" ::: "memory")
; #define PG8_WAIT_L(n) asm volatile("s_waitcnt lgkmcnt(" #n ")" ::: "memory")
; #define PG8_BAR __builtin_amdgcn_s_barrier()
; #define PG8_SCHED __builtin_amdgcn_sched_barrier(0)
; template <class Epi, class Sched, bool ALIGN_EPI = false, bool SP2 = false>
; __device__ __forceinline__ void gemm_phase(PG8_LAS unsigned char* lds, const Gemm g, const Sched& S, const Epi& E, const int tid_in) {
;     ...
;             PG8_LDB(B0, 1, 0); PG8_LDB(B1, 1, 1); PG8_SCHED; PG8_LDA(At, 1, 0); PG8_STAGE(PG8_SA(0, 1), a2 + hstepA, voffA);
;             PG8_WAIT_V(8); PG8_WAIT_L(0); PG8_BAR; PG8_MMA(0, 0, At, B0); PG8_MMA(0, 1, At, B1); PG8_BAR; PG8_SCHED;
;             PG8_LDA(At, 1, 1); PG8_STAGE(PG8_SB(1, 0), b3, voffB); PG8_STAGE(PG8_SB(1, 1), b3 + hstep, voffB); PG8_STAGE(PG8_SA(1, 0), a3, voffA);
;             PG8_WAIT_V(8); PG8_WAIT_L(0); PG8_BAR; PG8_MMA(1, 0, At, B0); PG8_MMA(1, 1, At, B1); PG8_BAR; PG8_SCHED;
	s_add_i32 s46, 0, 0x18000
	s_add_i32 s60, 0, 0x1c000
	v_add_u32_e32 v142, s46, v191
	v_add_u32_e32 v168, s60, v191
	ds_read_b128 v[114:117], v142
	ds_read_b128 v[134:137], v142 offset:1024
	ds_read_b128 v[138:141], v142 offset:2048
	ds_read_b128 v[142:145], v142 offset:3072
	ds_read_b128 v[146:149], v168
	ds_read_b128 v[150:153], v168 offset:1024
	ds_read_b128 v[154:157], v168 offset:2048
	ds_read_b128 v[168:171], v168 offset:3072
	s_add_u32 s40, s58, 0x80000
	s_addc_u32 s41, s59, 0
	s_mov_b32 m0, s73
	ds_read_b128 v[172:175], v193 offset:32768
	ds_read_b128 v[176:179], v193 offset:33792
	ds_read_b128 v[180:183], v193 offset:34816
	ds_read_b128 v[184:187], v193 offset:35840
	ds_read_b128 v[194:197], v193 offset:36864
	ds_read_b128 v[206:209], v193 offset:37888
	ds_read_b128 v[210:213], v193 offset:38912
	ds_read_b128 v[214:217], v193 offset:39936
	global_load_lds_dwordx4 v162, s[40:41]
	s_mov_b32 m0, s80
	s_nop 0
	global_load_lds_dwordx4 v160, s[40:41]
	s_waitcnt vmcnt(8)
	s_waitcnt lgkmcnt(0)
	s_barrier
	s_setprio 3
	s_waitcnt lgkmcnt(0)
	v_mfma_f32_16x16x32_bf16 v[126:129], v[114:117], v[172:175], v[126:129]
	v_mfma_f32_16x16x32_bf16 v[122:125], v[138:141], v[172:175], v[122:125]
	v_mfma_f32_16x16x32_bf16 v[110:113], v[114:117], v[180:183], v[110:113]
	v_mfma_f32_16x16x32_bf16 v[102:105], v[138:141], v[180:183], v[102:105]
	v_mfma_f32_16x16x32_bf16 v[94:97], v[114:117], v[194:197], v[94:97]
	v_mfma_f32_16x16x32_bf16 v[86:89], v[138:141], v[194:197], v[86:89]
	v_mfma_f32_16x16x32_bf16 v[78:81], v[114:117], v[210:213], v[78:81]
	v_mfma_f32_16x16x32_bf16 v[70:73], v[138:141], v[210:213], v[70:73]
	v_mfma_f32_16x16x32_bf16 v[126:129], v[134:137], v[176:179], v[126:129]
	v_mfma_f32_16x16x32_bf16 v[122:125], v[142:145], v[176:179], v[122:125]
	v_mfma_f32_16x16x32_bf16 v[110:113], v[134:137], v[184:187], v[110:113]
	v_mfma_f32_16x16x32_bf16 v[102:105], v[142:145], v[184:187], v[102:105]
	v_mfma_f32_16x16x32_bf16 v[94:97], v[134:137], v[206:209], v[94:97]
	v_mfma_f32_16x16x32_bf16 v[86:89], v[142:145], v[206:209], v[86:89]
	v_mfma_f32_16x16x32_bf16 v[78:81], v[134:137], v[214:217], v[78:81]
	v_mfma_f32_16x16x32_bf16 v[70:73], v[142:145], v[214:217], v[70:73]
	s_setprio 0
	s_setprio 3
	v_mfma_f32_16x16x32_bf16 v[130:133], v[146:149], v[172:175], v[130:133]
	v_mfma_f32_16x16x32_bf16 v[118:121], v[154:157], v[172:175], v[118:121]
	v_mfma_f32_16x16x32_bf16 v[106:109], v[146:149], v[180:183], v[106:109]
	v_mfma_f32_16x16x32_bf16 v[98:101], v[154:157], v[180:183], v[98:101]
	v_mfma_f32_16x16x32_bf16 v[90:93], v[146:149], v[194:197], v[90:93]
	v_mfma_f32_16x16x32_bf16 v[82:85], v[154:157], v[194:197], v[82:85]
	v_mfma_f32_16x16x32_bf16 v[74:77], v[146:149], v[210:213], v[74:77]
	v_mfma_f32_16x16x32_bf16 v[66:69], v[154:157], v[210:213], v[66:69]
	v_mfma_f32_16x16x32_bf16 v[130:133], v[150:153], v[176:179], v[130:133]
	v_mfma_f32_16x16x32_bf16 v[118:121], v[168:171], v[176:179], v[118:121]
	v_mfma_f32_16x16x32_bf16 v[106:109], v[150:153], v[184:187], v[106:109]
	v_mfma_f32_16x16x32_bf16 v[98:101], v[168:171], v[184:187], v[98:101]
	v_mfma_f32_16x16x32_bf16 v[90:93], v[150:153], v[206:209], v[90:93]
	v_mfma_f32_16x16x32_bf16 v[82:85], v[168:171], v[206:209], v[82:85]
	v_mfma_f32_16x16x32_bf16 v[74:77], v[150:153], v[214:217], v[74:77]
	v_mfma_f32_16x16x32_bf16 v[66:69], v[168:171], v[214:217], v[66:69]
	s_setprio 0
	s_barrier
	s_add_i32 s46, s46, s70
	s_mov_b32 m0, s46
	s_add_u32 s40, s22, 0x80
	s_addc_u32 s41, s23, 0
	ds_read_b128 v[172:175], v193 offset:49152
	ds_read_b128 v[176:179], v193 offset:50176
	ds_read_b128 v[180:183], v193 offset:51200
	ds_read_b128 v[184:187], v193 offset:52224
	ds_read_b128 v[194:197], v193 offset:53248
	ds_read_b128 v[206:209], v193 offset:54272
	ds_read_b128 v[210:213], v193 offset:55296
	ds_read_b128 v[214:217], v193 offset:56320
	global_load_lds_dwordx4 v64, s[40:41]
	s_add_i32 m0, s46, 0x2000
	s_add_u32 s22, s22, 0x80080
	s_addc_u32 s23, s23, 0
	s_add_i32 s60, s60, s70
	global_load_lds_dwordx4 v158, s[40:41]
	s_mov_b32 m0, s60
	s_nop 0
	global_load_lds_dwordx4 v64, s[22:23]
	s_add_i32 m0, s60, 0x2000
	s_add_u32 s40, s58, 0x80
	s_addc_u32 s41, s59, 0
	global_load_lds_dwordx4 v158, s[22:23]
	s_mov_b32 m0, s0
	s_nop 0
	global_load_lds_dwordx4 v162, s[40:41]
	s_mov_b32 m0, s1
	s_nop 0
	global_load_lds_dwordx4 v160, s[40:41]
	s_waitcnt vmcnt(8)
	s_waitcnt lgkmcnt(0)
	s_barrier
	s_setprio 3
	s_waitcnt lgkmcnt(0)
	v_mfma_f32_16x16x32_bf16 v[60:63], v[114:117], v[172:175], v[60:63]
	v_mfma_f32_16x16x32_bf16 v[52:55], v[138:141], v[172:175], v[52:55]
	v_mfma_f32_16x16x32_bf16 v[44:47], v[114:117], v[180:183], v[44:47]
	v_mfma_f32_16x16x32_bf16 v[36:39], v[138:141], v[180:183], v[36:39]
	v_mfma_f32_16x16x32_bf16 v[28:31], v[114:117], v[194:197], v[28:31]
	v_mfma_f32_16x16x32_bf16 v[20:23], v[138:141], v[194:197], v[20:23]
	v_mfma_f32_16x16x32_bf16 v[12:15], v[114:117], v[210:213], v[12:15]
	v_mfma_f32_16x16x32_bf16 v[4:7], v[138:141], v[210:213], v[4:7]
	v_mfma_f32_16x16x32_bf16 v[60:63], v[134:137], v[176:179], v[60:63]
	v_mfma_f32_16x16x32_bf16 v[52:55], v[142:145], v[176:179], v[52:55]
	v_mfma_f32_16x16x32_bf16 v[44:47], v[134:137], v[184:187], v[44:47]
	v_mfma_f32_16x16x32_bf16 v[36:39], v[142:145], v[184:187], v[36:39]
	v_mfma_f32_16x16x32_bf16 v[28:31], v[134:137], v[206:209], v[28:31]
	v_mfma_f32_16x16x32_bf16 v[20:23], v[142:145], v[206:209], v[20:23]
	v_mfma_f32_16x16x32_bf16 v[12:15], v[134:137], v[214:217], v[12:15]
	v_mfma_f32_16x16x32_bf16 v[4:7], v[142:145], v[214:217], v[4:7]
	s_setprio 0
	s_setprio 3
	v_mfma_f32_16x16x32_bf16 v[56:59], v[146:149], v[172:175], v[56:59]
	v_mfma_f32_16x16x32_bf16 v[48:51], v[154:157], v[172:175], v[48:51]
	v_mfma_f32_16x16x32_bf16 v[40:43], v[146:149], v[180:183], v[40:43]
	v_mfma_f32_16x16x32_bf16 v[32:35], v[154:157], v[180:183], v[32:35]
	v_mfma_f32_16x16x32_bf16 v[24:27], v[146:149], v[194:197], v[24:27]
	v_mfma_f32_16x16x32_bf16 v[16:19], v[154:157], v[194:197], v[16:19]
	v_mfma_f32_16x16x32_bf16 v[8:11], v[146:149], v[210:213], v[8:11]
	v_mfma_f32_16x16x32_bf16 v[0:3], v[154:157], v[210:213], v[0:3]
	v_mfma_f32_16x16x32_bf16 v[56:59], v[150:153], v[176:179], v[56:59]
	v_mfma_f32_16x16x32_bf16 v[48:51], v[168:171], v[176:179], v[48:51]
	v_mfma_f32_16x16x32_bf16 v[40:43], v[150:153], v[184:187], v[40:43]
	v_mfma_f32_16x16x32_bf16 v[32:35], v[168:171], v[184:187], v[32:35]
	v_mfma_f32_16x16x32_bf16 v[24:27], v[150:153], v[206:209], v[24:27]
	v_mfma_f32_16x16x32_bf16 v[16:19], v[168:171], v[206:209], v[16:19]
	v_mfma_f32_16x16x32_bf16 v[8:11], v[150:153], v[214:217], v[8:11]
	v_mfma_f32_16x16x32_bf16 v[0:3], v[168:171], v[214:217], v[0:3]
	s_setprio 0
	s_barrier
	s_add_i32 s81, s81, 2
	s_add_u32 s26, s26, 0x100
	s_addc_u32 s27, s27, 0
	s_add_u32 vcc_hi, vcc_hi, 0x100
	s_addc_u32 s61, s61, 0
	s_cmp_gt_u32 s81, 29
	s_cbranch_scc0 .LBB0_107
	v_readlane_b32 s22, v255, 18
	v_readlane_b32 s23, v255, 19
	s_and_b64 vcc, exec, s[22:23]
	s_cbranch_vccz .LBB0_110
	s_barrier

; #define PG8_STAGE(bufoff, gbase, voff) do { _Pragma("unroll") for (int _i = 0; _i < 2; ++_i) \
;         __builtin_amdgcn_global_load_lds((const unsigned*)((const char*)(gbase) + (voff)[_i]), (PG8_LAS unsigned*)(lds + (bufoff) + ldsw + _i * 8192), 16, 0, 0); } while (0)
; #define PG8_LDA(dst, b, h) do { _Pragma("unroll") for (int m = 0; m < 4; ++m) _Pragma("unroll") for (int k = 0; k < 2; ++k) dst[m][k] = *(const PG8_LAS bf16x8*)(lds + PG8_SA(b, h) + aoff + m * 2048 + k * 1024); } while (0)
; #define PG8_LDB(dst, b, h) do { _Pragma("unroll") for (int n = 0; n < 2; ++n) _Pragma("unroll") for (int k = 0; k < 2; ++k) dst[n][k] = *(const PG8_LAS bf16x8*)(lds + PG8_SB(b, h) + boff + n * 2048 + k * 1024); } while (0)
; #define PG8_MMA(ai, bj, At, Bt) do { __builtin_amdgcn_s_setprio(3); _Pragma("unroll") for (int m = 0; m < 4; ++m) _Pragma("unroll") for (int n = 0; n < 2; ++n) _Pragma("unroll") for (int k = 0; k < 2; ++k) \
;         acc[ai][bj][m][n] = __builtin_amdgcn_mfma_f32_16x16x32_bf16(Bt[n][k], At[m][k], acc[ai][bj][m][n], 0, 0, 0); __builtin_amdgcn_s_setprio(0); } while (0)
; #define PG8_WAIT_V(n) asm volatile("s_waitcnt vmcnt(" #n ")" ::: "memory")
; #define PG8_WAIT_L(n) asm volatile("s_waitcnt lgkmcnt(" #n ")" ::: "memory")
; #define PG8_BAR __builtin_amdgcn_s_barrier()
; #define PG8_SCHED __builtin_amdgcn_sched_barrier(0)
; template <class Epi, class Sched, bool ALIGN_EPI = false, bool SP2 = false>
; __device__ __forceinline__ void gemm_phase(PG8_LAS unsigned char* lds, const Gemm g, const Sched& S, const Epi& E, const int tid_in) {
;     ...
;             PG8_LDB(B0, 0, 0); PG8_LDB(B1, 0, 1); PG8_SCHED; PG8_LDA(At, 0, 0); PG8_STAGE(PG8_SA(1, 1), a1 + hstepA, voffA);
;             PG8_WAIT_V(8); PG8_WAIT_L(0); PG8_BAR; PG8_MMA(0, 0, At, B0); PG8_MMA(0, 1, At, B1); PG8_BAR; PG8_SCHED;
;             PG8_LDA(At, 0, 1); PG8_STAGE(PG8_SB(0, 0), b2, voffB); PG8_STAGE(PG8_SB(0, 1), b2 + hstep, voffB); PG8_STAGE(PG8_SA(0, 0), a2, voffA);
;             PG8_WAIT_V(8); PG8_WAIT_L(0); PG8_BAR; PG8_MMA(1, 0, At, B0); PG8_MMA(1, 1, At, B1); PG8_BAR; PG8_SCHED;
.LBB0_145:
	s_add_u32 s22, s26, 0xfff80080
	s_addc_u32 s23, s27, -1
	s_add_i32 s40, 0, 0x10000
	s_cmp_eq_u32 s81, 28
	s_cselect_b32 s59, s43, s23
	s_cselect_b32 s58, s47, s22
	s_cselect_b32 s23, s45, s61
	s_cselect_b32 s22, vcc_lo, vcc_hi
	s_add_i32 s46, 0, 0x14000
	v_add_u32_e32 v134, s40, v240
	v_add_u32_e32 v158, s46, v240
	ds_read_b128 v[114:117], v134
	ds_read_b128 v[118:121], v134 offset:1024
	ds_read_b128 v[126:129], v134 offset:2048
	ds_read_b128 v[134:137], v134 offset:3072
	ds_read_b128 v[138:141], v158
	ds_read_b128 v[142:145], v158 offset:1024
	ds_read_b128 v[154:157], v158 offset:2048
	ds_read_b128 v[158:161], v158 offset:3072
	s_add_i32 m0, s71, 0xc000
	ds_read_b128 v[162:165], v245
	ds_read_b128 v[166:169], v245 offset:1024
	ds_read_b128 v[170:173], v245 offset:2048
	ds_read_b128 v[174:177], v245 offset:3072
	ds_read_b128 v[178:181], v245 offset:4096
	ds_read_b128 v[182:185], v245 offset:5120
	ds_read_b128 v[186:189], v245 offset:6144
	ds_read_b128 v[190:193], v245 offset:7168
	global_load_lds_dwordx4 v212, s[26:27]
	s_add_i32 m0, s71, 0xe000
	s_nop 0
	global_load_lds_dwordx4 v214, s[26:27]
	s_waitcnt vmcnt(8)
	s_waitcnt lgkmcnt(0)
	s_barrier
	s_setprio 3
	s_waitcnt lgkmcnt(0)
	v_mfma_f32_16x16x32_bf16 v[150:153], v[114:117], v[162:165], v[150:153]
	v_mfma_f32_16x16x32_bf16 v[146:149], v[126:129], v[162:165], v[146:149]
	v_mfma_f32_16x16x32_bf16 v[110:113], v[114:117], v[170:173], v[110:113]
	v_mfma_f32_16x16x32_bf16 v[106:109], v[126:129], v[170:173], v[106:109]
	v_mfma_f32_16x16x32_bf16 v[94:97], v[114:117], v[178:181], v[94:97]
	v_mfma_f32_16x16x32_bf16 v[90:93], v[126:129], v[178:181], v[90:93]
	v_mfma_f32_16x16x32_bf16 v[78:81], v[114:117], v[186:189], v[78:81]
	v_mfma_f32_16x16x32_bf16 v[74:77], v[126:129], v[186:189], v[74:77]
	v_mfma_f32_16x16x32_bf16 v[150:153], v[118:121], v[166:169], v[150:153]
	v_mfma_f32_16x16x32_bf16 v[146:149], v[134:137], v[166:169], v[146:149]
	v_mfma_f32_16x16x32_bf16 v[110:113], v[118:121], v[174:177], v[110:113]
	v_mfma_f32_16x16x32_bf16 v[106:109], v[134:137], v[174:177], v[106:109]
	v_mfma_f32_16x16x32_bf16 v[94:97], v[118:121], v[182:185], v[94:97]
	v_mfma_f32_16x16x32_bf16 v[90:93], v[134:137], v[182:185], v[90:93]
	v_mfma_f32_16x16x32_bf16 v[78:81], v[118:121], v[190:193], v[78:81]
	v_mfma_f32_16x16x32_bf16 v[74:77], v[134:137], v[190:193], v[74:77]
	s_setprio 0
	s_setprio 3
	v_mfma_f32_16x16x32_bf16 v[130:133], v[138:141], v[162:165], v[130:133]
	v_mfma_f32_16x16x32_bf16 v[122:125], v[154:157], v[162:165], v[122:125]
	v_mfma_f32_16x16x32_bf16 v[102:105], v[138:141], v[170:173], v[102:105]
	v_mfma_f32_16x16x32_bf16 v[98:101], v[154:157], v[170:173], v[98:101]
	v_mfma_f32_16x16x32_bf16 v[86:89], v[138:141], v[178:181], v[86:89]
	v_mfma_f32_16x16x32_bf16 v[82:85], v[154:157], v[178:181], v[82:85]
	v_mfma_f32_16x16x32_bf16 v[70:73], v[138:141], v[186:189], v[70:73]
	v_mfma_f32_16x16x32_bf16 v[66:69], v[154:157], v[186:189], v[66:69]
	v_mfma_f32_16x16x32_bf16 v[130:133], v[142:145], v[166:169], v[130:133]
	v_mfma_f32_16x16x32_bf16 v[122:125], v[158:161], v[166:169], v[122:125]
	v_mfma_f32_16x16x32_bf16 v[102:105], v[142:145], v[174:177], v[102:105]
	v_mfma_f32_16x16x32_bf16 v[98:101], v[158:161], v[174:177], v[98:101]
	v_mfma_f32_16x16x32_bf16 v[86:89], v[142:145], v[182:185], v[86:89]
	v_mfma_f32_16x16x32_bf16 v[82:85], v[158:161], v[182:185], v[82:85]
	v_mfma_f32_16x16x32_bf16 v[70:73], v[142:145], v[190:193], v[70:73]
	v_mfma_f32_16x16x32_bf16 v[66:69], v[158:161], v[190:193], v[66:69]
	s_setprio 0
	s_barrier
	s_add_i32 s40, s40, s70
	s_mov_b32 m0, s40
	ds_read_b128 v[162:165], v245 offset:16384
	ds_read_b128 v[166:169], v245 offset:17408
	ds_read_b128 v[170:173], v245 offset:18432
	ds_read_b128 v[174:177], v245 offset:19456
	ds_read_b128 v[178:181], v245 offset:20480
	ds_read_b128 v[182:185], v245 offset:21504
	ds_read_b128 v[186:189], v245 offset:22528
	ds_read_b128 v[190:193], v245 offset:23552
	global_load_lds_dwordx4 v64, s[22:23]
	s_add_i32 m0, s40, 0x2000
	s_add_u32 s40, s22, 0x80000
	s_addc_u32 s41, s23, 0
	s_add_i32 s46, s46, s70
	global_load_lds_dwordx4 v206, s[22:23]
	s_mov_b32 m0, s46
	global_load_lds_dwordx4 v64, s[40:41]
	s_add_i32 m0, s46, 0x2000
	s_nop 0
	global_load_lds_dwordx4 v206, s[40:41]
	s_mov_b32 m0, s71
	s_nop 0
	global_load_lds_dwordx4 v210, s[58:59]
	s_mov_b32 m0, s72
	s_nop 0
	global_load_lds_dwordx4 v208, s[58:59]
	s_waitcnt vmcnt(8)
	s_waitcnt lgkmcnt(0)
	s_barrier
	s_setprio 3
	s_waitcnt lgkmcnt(0)
	v_mfma_f32_16x16x32_bf16 v[60:63], v[114:117], v[162:165], v[60:63]
	v_mfma_f32_16x16x32_bf16 v[56:59], v[126:129], v[162:165], v[56:59]
	v_mfma_f32_16x16x32_bf16 v[44:47], v[114:117], v[170:173], v[44:47]
	v_mfma_f32_16x16x32_bf16 v[40:43], v[126:129], v[170:173], v[40:43]
	v_mfma_f32_16x16x32_bf16 v[28:31], v[114:117], v[178:181], v[28:31]
	v_mfma_f32_16x16x32_bf16 v[24:27], v[126:129], v[178:181], v[24:27]
	v_mfma_f32_16x16x32_bf16 v[12:15], v[114:117], v[186:189], v[12:15]
	v_mfma_f32_16x16x32_bf16 v[8:11], v[126:129], v[186:189], v[8:11]
	v_mfma_f32_16x16x32_bf16 v[60:63], v[118:121], v[166:169], v[60:63]
	v_mfma_f32_16x16x32_bf16 v[56:59], v[134:137], v[166:169], v[56:59]
	v_mfma_f32_16x16x32_bf16 v[44:47], v[118:121], v[174:177], v[44:47]
	v_mfma_f32_16x16x32_bf16 v[40:43], v[134:137], v[174:177], v[40:43]
	v_mfma_f32_16x16x32_bf16 v[28:31], v[118:121], v[182:185], v[28:31]
	v_mfma_f32_16x16x32_bf16 v[24:27], v[134:137], v[182:185], v[24:27]
	v_mfma_f32_16x16x32_bf16 v[12:15], v[118:121], v[190:193], v[12:15]
	v_mfma_f32_16x16x32_bf16 v[8:11], v[134:137], v[190:193], v[8:11]
	s_setprio 0
	s_setprio 3
	v_mfma_f32_16x16x32_bf16 v[52:55], v[138:141], v[162:165], v[52:55]
	v_mfma_f32_16x16x32_bf16 v[48:51], v[154:157], v[162:165], v[48:51]
	v_mfma_f32_16x16x32_bf16 v[36:39], v[138:141], v[170:173], v[36:39]
	v_mfma_f32_16x16x32_bf16 v[32:35], v[154:157], v[170:173], v[32:35]
	v_mfma_f32_16x16x32_bf16 v[20:23], v[138:141], v[178:181], v[20:23]
	v_mfma_f32_16x16x32_bf16 v[16:19], v[154:157], v[178:181], v[16:19]
	v_mfma_f32_16x16x32_bf16 v[4:7], v[138:141], v[186:189], v[4:7]
	v_mfma_f32_16x16x32_bf16 v[0:3], v[154:157], v[186:189], v[0:3]
	v_mfma_f32_16x16x32_bf16 v[52:55], v[142:145], v[166:169], v[52:55]
	v_mfma_f32_16x16x32_bf16 v[48:51], v[158:161], v[166:169], v[48:51]
	v_mfma_f32_16x16x32_bf16 v[36:39], v[142:145], v[174:177], v[36:39]
	v_mfma_f32_16x16x32_bf16 v[32:35], v[158:161], v[174:177], v[32:35]
	v_mfma_f32_16x16x32_bf16 v[20:23], v[142:145], v[182:185], v[20:23]
	v_mfma_f32_16x16x32_bf16 v[16:19], v[158:161], v[182:185], v[16:19]
	v_mfma_f32_16x16x32_bf16 v[4:7], v[142:145], v[190:193], v[4:7]
	v_mfma_f32_16x16x32_bf16 v[0:3], v[158:161], v[190:193], v[0:3]
	s_setprio 0
	s_barrier
; #define PG8_STAGE(bufoff, gbase, voff) do { _Pragma("unroll") for (int _i = 0; _i < 2; ++_i) \
;         __builtin_amdgcn_global_load_lds((const unsigned*)((const char*)(gbase) + (voff)[_i]), (PG8_LAS unsigned*)(lds + (bufoff) + ldsw + _i * 8192), 16, 0, 0); } while (0)
; #define PG8_LDA(dst, b, h) do { _Pragma("unroll") for (int m = 0; m < 4; ++m) _Pragma("unroll") for (int k = 0; k < 2; ++k) dst[m][k] = *(const PG8_LAS bf16x8*)(lds + PG8_SA(b, h) + aoff + m * 2048 + k * 1024); } while (0)
; #define PG8_LDB(dst, b, h) do { _Pragma("unroll") for (int n = 0; n < 2; ++n) _Pragma("unroll") for (int k = 0; k < 2; ++k) dst[n][k] = *(const PG8_LAS bf16x8*)(lds + PG8_SB(b, h) + boff + n * 2048 + k * 1024); } while (0)
; #define PG8_MMA(ai, bj, At, Bt) do { __builtin_amdgcn_s_setprio(3); _Pragma("unroll") for (int m = 0; m < 4; ++m) _Pragma("unroll") for (int n = 0; n < 2; ++n) _Pragma("unroll") for (int k = 0; k < 2; ++k) \
;         acc[ai][bj][m][n] = __builtin_amdgcn_mfma_f32_16x16x32_bf16(Bt[n][k], At[m][k], acc[ai][bj][m][n], 0, 0, 0); __builtin_amdgcn_s_setprio(0); } while (0)
; #define PG8_WAIT_V(n) asm volatile("s_waitcnt vmcnt(" #n ")" ::: "memory")
; #define PG8_WAIT_L(n) asm volatile("s_waitcnt lgkmcnt(" #n ")" ::: "memory")
; #define PG8_BAR __builtin_amdgcn_s_barrier()
; #define PG8_SCHED __builtin_amdgcn_sched_barrier(0)
; template <class Epi, class Sched, bool ALIGN_EPI = false, bool SP2 = false>
; __device__ __forceinline__ void gemm_phase(PG8_LAS unsigned char* lds, const Gemm g, const Sched& S, const Epi& E, const int tid_in) {
;     ...
;             PG8_LDB(B0, 1, 0); PG8_LDB(B1, 1, 1); PG8_SCHED; PG8_LDA(At, 1, 0); PG8_STAGE(PG8_SA(0, 1), a2 + hstepA, voffA);
;             PG8_WAIT_V(8); PG8_WAIT_L(0); PG8_BAR; PG8_MMA(0, 0, At, B0); PG8_MMA(0, 1, At, B1); PG8_BAR; PG8_SCHED;
;             PG8_LDA(At, 1, 1); PG8_STAGE(PG8_SB(1, 0), b3, voffB); PG8_STAGE(PG8_SB(1, 1), b3 + hstep, voffB); PG8_STAGE(PG8_SA(1, 0), a3, voffA);
;             PG8_WAIT_V(8); PG8_WAIT_L(0); PG8_BAR; PG8_MMA(1, 0, At, B0); PG8_MMA(1, 1, At, B1); PG8_BAR; PG8_SCHED;
	s_add_i32 s46, 0, 0x18000
	s_add_i32 s60, 0, 0x1c000
	v_add_u32_e32 v134, s46, v240
	v_add_u32_e32 v158, s60, v240
	ds_read_b128 v[114:117], v134
	ds_read_b128 v[118:121], v134 offset:1024
	ds_read_b128 v[126:129], v134 offset:2048
	ds_read_b128 v[134:137], v134 offset:3072
	ds_read_b128 v[138:141], v158
	ds_read_b128 v[142:145], v158 offset:1024
	ds_read_b128 v[154:157], v158 offset:2048
	ds_read_b128 v[158:161], v158 offset:3072
	s_add_u32 s40, s58, 0x80000
	s_addc_u32 s41, s59, 0
	s_mov_b32 m0, s73
	ds_read_b128 v[162:165], v245 offset:32768
	ds_read_b128 v[166:169], v245 offset:33792
	ds_read_b128 v[170:173], v245 offset:34816
	ds_read_b128 v[174:177], v245 offset:35840
	ds_read_b128 v[178:181], v245 offset:36864
	ds_read_b128 v[182:185], v245 offset:37888
	ds_read_b128 v[186:189], v245 offset:38912
	ds_read_b128 v[190:193], v245 offset:39936
	global_load_lds_dwordx4 v210, s[40:41]
	s_mov_b32 m0, s80
	s_nop 0
	global_load_lds_dwordx4 v208, s[40:41]
	s_waitcnt vmcnt(8)
	s_waitcnt lgkmcnt(0)
	s_barrier
	s_setprio 3
	s_waitcnt lgkmcnt(0)
	v_mfma_f32_16x16x32_bf16 v[150:153], v[114:117], v[162:165], v[150:153]
	v_mfma_f32_16x16x32_bf16 v[146:149], v[126:129], v[162:165], v[146:149]
	v_mfma_f32_16x16x32_bf16 v[110:113], v[114:117], v[170:173], v[110:113]
	v_mfma_f32_16x16x32_bf16 v[106:109], v[126:129], v[170:173], v[106:109]
	v_mfma_f32_16x16x32_bf16 v[94:97], v[114:117], v[178:181], v[94:97]
	v_mfma_f32_16x16x32_bf16 v[90:93], v[126:129], v[178:181], v[90:93]
	v_mfma_f32_16x16x32_bf16 v[78:81], v[114:117], v[186:189], v[78:81]
	v_mfma_f32_16x16x32_bf16 v[74:77], v[126:129], v[186:189], v[74:77]
	v_mfma_f32_16x16x32_bf16 v[150:153], v[118:121], v[166:169], v[150:153]
	v_mfma_f32_16x16x32_bf16 v[146:149], v[134:137], v[166:169], v[146:149]
	v_mfma_f32_16x16x32_bf16 v[110:113], v[118:121], v[174:177], v[110:113]
	v_mfma_f32_16x16x32_bf16 v[106:109], v[134:137], v[174:177], v[106:109]
	v_mfma_f32_16x16x32_bf16 v[94:97], v[118:121], v[182:185], v[94:97]
	v_mfma_f32_16x16x32_bf16 v[90:93], v[134:137], v[182:185], v[90:93]
	v_mfma_f32_16x16x32_bf16 v[78:81], v[118:121], v[190:193], v[78:81]
	v_mfma_f32_16x16x32_bf16 v[74:77], v[134:137], v[190:193], v[74:77]
	s_setprio 0
	s_setprio 3
	v_mfma_f32_16x16x32_bf16 v[130:133], v[138:141], v[162:165], v[130:133]
	v_mfma_f32_16x16x32_bf16 v[122:125], v[154:157], v[162:165], v[122:125]
	v_mfma_f32_16x16x32_bf16 v[102:105], v[138:141], v[170:173], v[102:105]
	v_mfma_f32_16x16x32_bf16 v[98:101], v[154:157], v[170:173], v[98:101]
	v_mfma_f32_16x16x32_bf16 v[86:89], v[138:141], v[178:181], v[86:89]
	v_mfma_f32_16x16x32_bf16 v[82:85], v[154:157], v[178:181], v[82:85]
	v_mfma_f32_16x16x32_bf16 v[70:73], v[138:141], v[186:189], v[70:73]
	v_mfma_f32_16x16x32_bf16 v[66:69], v[154:157], v[186:189], v[66:69]
	v_mfma_f32_16x16x32_bf16 v[130:133], v[142:145], v[166:169], v[130:133]
	v_mfma_f32_16x16x32_bf16 v[122:125], v[158:161], v[166:169], v[122:125]
	v_mfma_f32_16x16x32_bf16 v[102:105], v[142:145], v[174:177], v[102:105]
	v_mfma_f32_16x16x32_bf16 v[98:101], v[158:161], v[174:177], v[98:101]
	v_mfma_f32_16x16x32_bf16 v[86:89], v[142:145], v[182:185], v[86:89]
	v_mfma_f32_16x16x32_bf16 v[82:85], v[158:161], v[182:185], v[82:85]
	v_mfma_f32_16x16x32_bf16 v[70:73], v[142:145], v[190:193], v[70:73]
	v_mfma_f32_16x16x32_bf16 v[66:69], v[158:161], v[190:193], v[66:69]
	s_setprio 0
	s_barrier
	s_add_i32 s46, s46, s70
	s_mov_b32 m0, s46
	s_add_u32 s40, s22, 0x80
	s_addc_u32 s41, s23, 0
	ds_read_b128 v[162:165], v245 offset:49152
	ds_read_b128 v[166:169], v245 offset:50176
	ds_read_b128 v[170:173], v245 offset:51200
	ds_read_b128 v[174:177], v245 offset:52224
	ds_read_b128 v[178:181], v245 offset:53248
	ds_read_b128 v[182:185], v245 offset:54272
	ds_read_b128 v[186:189], v245 offset:55296
	ds_read_b128 v[190:193], v245 offset:56320
	global_load_lds_dwordx4 v64, s[40:41]
	s_add_i32 m0, s46, 0x2000
	s_add_u32 s22, s22, 0x80080
	s_addc_u32 s23, s23, 0
	s_add_i32 s60, s60, s70
	global_load_lds_dwordx4 v206, s[40:41]
	s_mov_b32 m0, s60
	s_nop 0
	global_load_lds_dwordx4 v64, s[22:23]
	s_add_i32 m0, s60, 0x2000
	s_add_u32 s40, s58, 0x80
	s_addc_u32 s41, s59, 0
	global_load_lds_dwordx4 v206, s[22:23]
	s_mov_b32 m0, s0
	s_nop 0
	global_load_lds_dwordx4 v210, s[40:41]
	s_mov_b32 m0, s1
	s_nop 0
	global_load_lds_dwordx4 v208, s[40:41]
	s_waitcnt vmcnt(8)
	s_waitcnt lgkmcnt(0)
	s_barrier
	s_setprio 3
	s_waitcnt lgkmcnt(0)
	v_mfma_f32_16x16x32_bf16 v[60:63], v[114:117], v[162:165], v[60:63]
	v_mfma_f32_16x16x32_bf16 v[56:59], v[126:129], v[162:165], v[56:59]
	v_mfma_f32_16x16x32_bf16 v[44:47], v[114:117], v[170:173], v[44:47]
	v_mfma_f32_16x16x32_bf16 v[40:43], v[126:129], v[170:173], v[40:43]
	v_mfma_f32_16x16x32_bf16 v[28:31], v[114:117], v[178:181], v[28:31]
	v_mfma_f32_16x16x32_bf16 v[24:27], v[126:129], v[178:181], v[24:27]
	v_mfma_f32_16x16x32_bf16 v[12:15], v[114:117], v[186:189], v[12:15]
	v_mfma_f32_16x16x32_bf16 v[8:11], v[126:129], v[186:189], v[8:11]
	v_mfma_f32_16x16x32_bf16 v[60:63], v[118:121], v[166:169], v[60:63]
	v_mfma_f32_16x16x32_bf16 v[56:59], v[134:137], v[166:169], v[56:59]
	v_mfma_f32_16x16x32_bf16 v[44:47], v[118:121], v[174:177], v[44:47]
	v_mfma_f32_16x16x32_bf16 v[40:43], v[134:137], v[174:177], v[40:43]
	v_mfma_f32_16x16x32_bf16 v[28:31], v[118:121], v[182:185], v[28:31]
	v_mfma_f32_16x16x32_bf16 v[24:27], v[134:137], v[182:185], v[24:27]
	v_mfma_f32_16x16x32_bf16 v[12:15], v[118:121], v[190:193], v[12:15]
	v_mfma_f32_16x16x32_bf16 v[8:11], v[134:137], v[190:193], v[8:11]
	s_setprio 0
	s_setprio 3
	v_mfma_f32_16x16x32_bf16 v[52:55], v[138:141], v[162:165], v[52:55]
	v_mfma_f32_16x16x32_bf16 v[48:51], v[154:157], v[162:165], v[48:51]
	v_mfma_f32_16x16x32_bf16 v[36:39], v[138:141], v[170:173], v[36:39]
	v_mfma_f32_16x16x32_bf16 v[32:35], v[154:157], v[170:173], v[32:35]
	v_mfma_f32_16x16x32_bf16 v[20:23], v[138:141], v[178:181], v[20:23]
	v_mfma_f32_16x16x32_bf16 v[16:19], v[154:157], v[178:181], v[16:19]
	v_mfma_f32_16x16x32_bf16 v[4:7], v[138:141], v[186:189], v[4:7]
	v_mfma_f32_16x16x32_bf16 v[0:3], v[154:157], v[186:189], v[0:3]
	v_mfma_f32_16x16x32_bf16 v[52:55], v[142:145], v[166:169], v[52:55]
	v_mfma_f32_16x16x32_bf16 v[48:51], v[158:161], v[166:169], v[48:51]
	v_mfma_f32_16x16x32_bf16 v[36:39], v[142:145], v[174:177], v[36:39]
	v_mfma_f32_16x16x32_bf16 v[32:35], v[158:161], v[174:177], v[32:35]
	v_mfma_f32_16x16x32_bf16 v[20:23], v[142:145], v[182:185], v[20:23]
	v_mfma_f32_16x16x32_bf16 v[16:19], v[158:161], v[182:185], v[16:19]
	v_mfma_f32_16x16x32_bf16 v[4:7], v[142:145], v[190:193], v[4:7]
	v_mfma_f32_16x16x32_bf16 v[0:3], v[158:161], v[190:193], v[0:3]
	s_setprio 0
	s_barrier
	s_add_i32 s81, s81, 2
	s_add_u32 s26, s26, 0x100
	s_addc_u32 s27, s27, 0
	s_add_u32 vcc_hi, vcc_hi, 0x100
	s_addc_u32 s61, s61, 0
	s_cmp_gt_u32 s81, 29
	s_cbranch_scc0 .LBB0_145
	v_readlane_b32 s22, v255, 18
	v_readlane_b32 s23, v255, 19
	s_and_b64 vcc, exec, s[22:23]
	s_cbranch_vccz .LBB0_148
	s_barrier

; #define PG8_STAGE(bufoff, gbase, voff) do { _Pragma("unroll") for (int _i = 0; _i < 2; ++_i) \
;         __builtin_amdgcn_global_load_lds((const unsigned*)((const char*)(gbase) + (voff)[_i]), (PG8_LAS unsigned*)(lds + (bufoff) + ldsw + _i * 8192), 16, 0, 0); } while (0)
; #define PG8_LDA(dst, b, h) do { _Pragma("unroll") for (int m = 0; m < 4; ++m) _Pragma("unroll") for (int k = 0; k < 2; ++k) dst[m][k] = *(const PG8_LAS bf16x8*)(lds + PG8_SA(b, h) + aoff + m * 2048 + k * 1024); } while (0)
; #define PG8_LDB(dst, b, h) do { _Pragma("unroll") for (int n = 0; n < 2; ++n) _Pragma("unroll") for (int k = 0; k < 2; ++k) dst[n][k] = *(const PG8_LAS bf16x8*)(lds + PG8_SB(b, h) + boff + n * 2048 + k * 1024); } while (0)
; #define PG8_MMA(ai, bj, At, Bt) do { __builtin_amdgcn_s_setprio(3); _Pragma("unroll") for (int m = 0; m < 4; ++m) _Pragma("unroll") for (int n = 0; n < 2; ++n) _Pragma("unroll") for (int k = 0; k < 2; ++k) \
;         acc[ai][bj][m][n] = __builtin_amdgcn_mfma_f32_16x16x32_bf16(Bt[n][k], At[m][k], acc[ai][bj][m][n], 0, 0, 0); __builtin_amdgcn_s_setprio(0); } while (0)
; #define PG8_WAIT_V(n) asm volatile("s_waitcnt vmcnt(" #n ")" ::: "memory")
; #define PG8_WAIT_L(n) asm volatile("s_waitcnt lgkmcnt(" #n ")" ::: "memory")
; #define PG8_BAR __builtin_amdgcn_s_barrier()
; #define PG8_SCHED __builtin_amdgcn_sched_barrier(0)
; template <class Epi, class Sched, bool ALIGN_EPI = false, bool SP2 = false>
; __device__ __forceinline__ void gemm_phase(PG8_LAS unsigned char* lds, const Gemm g, const Sched& S, const Epi& E, const int tid_in) {
;     ...
;             PG8_LDB(B0, 0, 0); PG8_LDB(B1, 0, 1); PG8_SCHED; PG8_LDA(At, 0, 0); PG8_STAGE(PG8_SA(1, 1), a1 + hstepA, voffA);
;             PG8_WAIT_V(8); PG8_WAIT_L(0); PG8_BAR; PG8_MMA(0, 0, At, B0); PG8_MMA(0, 1, At, B1); PG8_BAR; PG8_SCHED;
;             PG8_LDA(At, 0, 1); PG8_STAGE(PG8_SB(0, 0), b2, voffB); PG8_STAGE(PG8_SB(0, 1), b2 + hstep, voffB); PG8_STAGE(PG8_SA(0, 0), a2, voffA);
;             PG8_WAIT_V(8); PG8_WAIT_L(0); PG8_BAR; PG8_MMA(1, 0, At, B0); PG8_MMA(1, 1, At, B1); PG8_BAR; PG8_SCHED;
.LBB0_260:
	s_add_u32 s22, s26, 0x100
	s_addc_u32 s23, s27, 0
	s_add_i32 s43, 0, 0x10000
	s_cmpk_eq_i32 vcc_hi, 0x54
	s_cselect_b32 s57, s1, s23
	s_cselect_b32 s56, s0, s22
	s_cselect_b32 s55, s47, vcc_lo
	s_cselect_b32 s54, s46, s45
	s_add_i32 s44, 0, 0x14000
	v_add_u32_e32 v134, s43, v244
	v_add_u32_e32 v158, s44, v244
	ds_read_b128 v[114:117], v134
	ds_read_b128 v[118:121], v134 offset:1024
	ds_read_b128 v[130:133], v134 offset:2048
	ds_read_b128 v[134:137], v134 offset:3072
	ds_read_b128 v[138:141], v158
	ds_read_b128 v[142:145], v158 offset:1024
	ds_read_b128 v[154:157], v158 offset:2048
	ds_read_b128 v[158:161], v158 offset:3072
	s_add_i32 m0, s61, 0xc000
	ds_read_b128 v[162:165], v245
	ds_read_b128 v[166:169], v245 offset:1024
	ds_read_b128 v[170:173], v245 offset:2048
	ds_read_b128 v[174:177], v245 offset:3072
	ds_read_b128 v[178:181], v245 offset:4096
	ds_read_b128 v[182:185], v245 offset:5120
	ds_read_b128 v[186:189], v245 offset:6144
	ds_read_b128 v[190:193], v245 offset:7168
	global_load_lds_dwordx4 v212, s[26:27]
	s_add_i32 m0, s61, 0xe000
	s_nop 0
	global_load_lds_dwordx4 v214, s[26:27]
	s_waitcnt vmcnt(8)
	s_waitcnt lgkmcnt(0)
	s_barrier
	s_setprio 3
	s_waitcnt lgkmcnt(0)
	v_mfma_f32_16x16x32_bf16 v[150:153], v[114:117], v[162:165], v[150:153]
	v_mfma_f32_16x16x32_bf16 v[146:149], v[130:133], v[162:165], v[146:149]
	v_mfma_f32_16x16x32_bf16 v[110:113], v[114:117], v[170:173], v[110:113]
	v_mfma_f32_16x16x32_bf16 v[106:109], v[130:133], v[170:173], v[106:109]
	v_mfma_f32_16x16x32_bf16 v[94:97], v[114:117], v[178:181], v[94:97]
	v_mfma_f32_16x16x32_bf16 v[90:93], v[130:133], v[178:181], v[90:93]
	v_mfma_f32_16x16x32_bf16 v[78:81], v[114:117], v[186:189], v[78:81]
	v_mfma_f32_16x16x32_bf16 v[74:77], v[130:133], v[186:189], v[74:77]
	v_mfma_f32_16x16x32_bf16 v[150:153], v[118:121], v[166:169], v[150:153]
	v_mfma_f32_16x16x32_bf16 v[146:149], v[134:137], v[166:169], v[146:149]
	v_mfma_f32_16x16x32_bf16 v[110:113], v[118:121], v[174:177], v[110:113]
	v_mfma_f32_16x16x32_bf16 v[106:109], v[134:137], v[174:177], v[106:109]
	v_mfma_f32_16x16x32_bf16 v[94:97], v[118:121], v[182:185], v[94:97]
	v_mfma_f32_16x16x32_bf16 v[90:93], v[134:137], v[182:185], v[90:93]
	v_mfma_f32_16x16x32_bf16 v[78:81], v[118:121], v[190:193], v[78:81]
	v_mfma_f32_16x16x32_bf16 v[74:77], v[134:137], v[190:193], v[74:77]
	s_setprio 0
	s_setprio 3
	v_mfma_f32_16x16x32_bf16 v[126:129], v[138:141], v[162:165], v[126:129]
	v_mfma_f32_16x16x32_bf16 v[122:125], v[154:157], v[162:165], v[122:125]
	v_mfma_f32_16x16x32_bf16 v[102:105], v[138:141], v[170:173], v[102:105]
	v_mfma_f32_16x16x32_bf16 v[98:101], v[154:157], v[170:173], v[98:101]
	v_mfma_f32_16x16x32_bf16 v[86:89], v[138:141], v[178:181], v[86:89]
	v_mfma_f32_16x16x32_bf16 v[82:85], v[154:157], v[178:181], v[82:85]
	v_mfma_f32_16x16x32_bf16 v[70:73], v[138:141], v[186:189], v[70:73]
	v_mfma_f32_16x16x32_bf16 v[66:69], v[154:157], v[186:189], v[66:69]
	v_mfma_f32_16x16x32_bf16 v[126:129], v[142:145], v[166:169], v[126:129]
	v_mfma_f32_16x16x32_bf16 v[122:125], v[158:161], v[166:169], v[122:125]
	v_mfma_f32_16x16x32_bf16 v[102:105], v[142:145], v[174:177], v[102:105]
	v_mfma_f32_16x16x32_bf16 v[98:101], v[158:161], v[174:177], v[98:101]
	v_mfma_f32_16x16x32_bf16 v[86:89], v[142:145], v[182:185], v[86:89]
	v_mfma_f32_16x16x32_bf16 v[82:85], v[158:161], v[182:185], v[82:85]
	v_mfma_f32_16x16x32_bf16 v[70:73], v[142:145], v[190:193], v[70:73]
	v_mfma_f32_16x16x32_bf16 v[66:69], v[158:161], v[190:193], v[66:69]
	s_setprio 0
	s_barrier
	s_add_i32 s26, s43, s60
	s_mov_b32 m0, s26
	ds_read_b128 v[162:165], v245 offset:16384
	ds_read_b128 v[166:169], v245 offset:17408
	ds_read_b128 v[170:173], v245 offset:18432
	ds_read_b128 v[174:177], v245 offset:19456
	ds_read_b128 v[178:181], v245 offset:20480
	ds_read_b128 v[182:185], v245 offset:21504
	ds_read_b128 v[186:189], v245 offset:22528
	ds_read_b128 v[190:193], v245 offset:23552
	global_load_lds_dwordx4 v64, s[54:55]
	s_add_i32 m0, s26, 0x2000
	s_add_u32 s26, s54, 0x160000
	s_addc_u32 s27, s55, 0
	s_add_i32 s43, s44, s60
	global_load_lds_dwordx4 v206, s[54:55]
	s_mov_b32 m0, s43
	global_load_lds_dwordx4 v64, s[26:27]
	s_add_i32 m0, s43, 0x2000
	s_nop 0
	global_load_lds_dwordx4 v206, s[26:27]
	s_mov_b32 m0, s61
	s_nop 0
	global_load_lds_dwordx4 v210, s[56:57]
	s_mov_b32 m0, s70
	s_nop 0
	global_load_lds_dwordx4 v208, s[56:57]
	s_waitcnt vmcnt(8)
	s_waitcnt lgkmcnt(0)
	s_barrier
	s_setprio 3
	s_waitcnt lgkmcnt(0)
	v_mfma_f32_16x16x32_bf16 v[60:63], v[114:117], v[162:165], v[60:63]
	v_mfma_f32_16x16x32_bf16 v[56:59], v[130:133], v[162:165], v[56:59]
	v_mfma_f32_16x16x32_bf16 v[44:47], v[114:117], v[170:173], v[44:47]
	v_mfma_f32_16x16x32_bf16 v[40:43], v[130:133], v[170:173], v[40:43]
	v_mfma_f32_16x16x32_bf16 v[28:31], v[114:117], v[178:181], v[28:31]
	v_mfma_f32_16x16x32_bf16 v[24:27], v[130:133], v[178:181], v[24:27]
	v_mfma_f32_16x16x32_bf16 v[12:15], v[114:117], v[186:189], v[12:15]
	v_mfma_f32_16x16x32_bf16 v[8:11], v[130:133], v[186:189], v[8:11]
	v_mfma_f32_16x16x32_bf16 v[60:63], v[118:121], v[166:169], v[60:63]
	v_mfma_f32_16x16x32_bf16 v[56:59], v[134:137], v[166:169], v[56:59]
	v_mfma_f32_16x16x32_bf16 v[44:47], v[118:121], v[174:177], v[44:47]
	v_mfma_f32_16x16x32_bf16 v[40:43], v[134:137], v[174:177], v[40:43]
	v_mfma_f32_16x16x32_bf16 v[28:31], v[118:121], v[182:185], v[28:31]
	v_mfma_f32_16x16x32_bf16 v[24:27], v[134:137], v[182:185], v[24:27]
	v_mfma_f32_16x16x32_bf16 v[12:15], v[118:121], v[190:193], v[12:15]
	v_mfma_f32_16x16x32_bf16 v[8:11], v[134:137], v[190:193], v[8:11]
	s_setprio 0
	s_setprio 3
	v_mfma_f32_16x16x32_bf16 v[52:55], v[138:141], v[162:165], v[52:55]
	v_mfma_f32_16x16x32_bf16 v[48:51], v[154:157], v[162:165], v[48:51]
	v_mfma_f32_16x16x32_bf16 v[36:39], v[138:141], v[170:173], v[36:39]
	v_mfma_f32_16x16x32_bf16 v[32:35], v[154:157], v[170:173], v[32:35]
	v_mfma_f32_16x16x32_bf16 v[20:23], v[138:141], v[178:181], v[20:23]
	v_mfma_f32_16x16x32_bf16 v[16:19], v[154:157], v[178:181], v[16:19]
	v_mfma_f32_16x16x32_bf16 v[4:7], v[138:141], v[186:189], v[4:7]
	v_mfma_f32_16x16x32_bf16 v[0:3], v[154:157], v[186:189], v[0:3]
	v_mfma_f32_16x16x32_bf16 v[52:55], v[142:145], v[166:169], v[52:55]
	v_mfma_f32_16x16x32_bf16 v[48:51], v[158:161], v[166:169], v[48:51]
	v_mfma_f32_16x16x32_bf16 v[36:39], v[142:145], v[174:177], v[36:39]
	v_mfma_f32_16x16x32_bf16 v[32:35], v[158:161], v[174:177], v[32:35]
	v_mfma_f32_16x16x32_bf16 v[20:23], v[142:145], v[182:185], v[20:23]
	v_mfma_f32_16x16x32_bf16 v[16:19], v[158:161], v[182:185], v[16:19]
	v_mfma_f32_16x16x32_bf16 v[4:7], v[142:145], v[190:193], v[4:7]
	v_mfma_f32_16x16x32_bf16 v[0:3], v[158:161], v[190:193], v[0:3]
	s_setprio 0
	s_barrier
; #define PG8_STAGE(bufoff, gbase, voff) do { _Pragma("unroll") for (int _i = 0; _i < 2; ++_i) \
;         __builtin_amdgcn_global_load_lds((const unsigned*)((const char*)(gbase) + (voff)[_i]), (PG8_LAS unsigned*)(lds + (bufoff) + ldsw + _i * 8192), 16, 0, 0); } while (0)
; #define PG8_LDA(dst, b, h) do { _Pragma("unroll") for (int m = 0; m < 4; ++m) _Pragma("unroll") for (int k = 0; k < 2; ++k) dst[m][k] = *(const PG8_LAS bf16x8*)(lds + PG8_SA(b, h) + aoff + m * 2048 + k * 1024); } while (0)
; #define PG8_LDB(dst, b, h) do { _Pragma("unroll") for (int n = 0; n < 2; ++n) _Pragma("unroll") for (int k = 0; k < 2; ++k) dst[n][k] = *(const PG8_LAS bf16x8*)(lds + PG8_SB(b, h) + boff + n * 2048 + k * 1024); } while (0)
; #define PG8_MMA(ai, bj, At, Bt) do { __builtin_amdgcn_s_setprio(3); _Pragma("unroll") for (int m = 0; m < 4; ++m) _Pragma("unroll") for (int n = 0; n < 2; ++n) _Pragma("unroll") for (int k = 0; k < 2; ++k) \
;         acc[ai][bj][m][n] = __builtin_amdgcn_mfma_f32_16x16x32_bf16(Bt[n][k], At[m][k], acc[ai][bj][m][n], 0, 0, 0); __builtin_amdgcn_s_setprio(0); } while (0)
; #define PG8_WAIT_V(n) asm volatile("s_waitcnt vmcnt(" #n ")" ::: "memory")
; #define PG8_WAIT_L(n) asm volatile("s_waitcnt lgkmcnt(" #n ")" ::: "memory")
; #define PG8_BAR __builtin_amdgcn_s_barrier()
; #define PG8_SCHED __builtin_amdgcn_sched_barrier(0)
; template <class Epi, class Sched, bool ALIGN_EPI = false, bool SP2 = false>
; __device__ __forceinline__ void gemm_phase(PG8_LAS unsigned char* lds, const Gemm g, const Sched& S, const Epi& E, const int tid_in) {
;     ...
;             PG8_LDB(B0, 1, 0); PG8_LDB(B1, 1, 1); PG8_SCHED; PG8_LDA(At, 1, 0); PG8_STAGE(PG8_SA(0, 1), a2 + hstepA, voffA);
;             PG8_WAIT_V(8); PG8_WAIT_L(0); PG8_BAR; PG8_MMA(0, 0, At, B0); PG8_MMA(0, 1, At, B1); PG8_BAR; PG8_SCHED;
;             PG8_LDA(At, 1, 1); PG8_STAGE(PG8_SB(1, 0), b3, voffB); PG8_STAGE(PG8_SB(1, 1), b3 + hstep, voffB); PG8_STAGE(PG8_SA(1, 0), a3, voffA);
;             PG8_WAIT_V(8); PG8_WAIT_L(0); PG8_BAR; PG8_MMA(1, 0, At, B0); PG8_MMA(1, 1, At, B1); PG8_BAR; PG8_SCHED;
	s_add_i32 s43, 0, 0x18000
	s_add_i32 s44, 0, 0x1c000
	v_add_u32_e32 v134, s43, v244
	v_add_u32_e32 v158, s44, v244
	ds_read_b128 v[114:117], v134
	ds_read_b128 v[118:121], v134 offset:1024
	ds_read_b128 v[130:133], v134 offset:2048
	ds_read_b128 v[134:137], v134 offset:3072
	ds_read_b128 v[138:141], v158
	ds_read_b128 v[142:145], v158 offset:1024
	ds_read_b128 v[154:157], v158 offset:2048
	ds_read_b128 v[158:161], v158 offset:3072
	s_add_u32 s26, s56, 0x160000
	s_addc_u32 s27, s57, 0
	s_mov_b32 m0, s71
	ds_read_b128 v[162:165], v245 offset:32768
	ds_read_b128 v[166:169], v245 offset:33792
	ds_read_b128 v[170:173], v245 offset:34816
	ds_read_b128 v[174:177], v245 offset:35840
	ds_read_b128 v[178:181], v245 offset:36864
	ds_read_b128 v[182:185], v245 offset:37888
	ds_read_b128 v[186:189], v245 offset:38912
	ds_read_b128 v[190:193], v245 offset:39936
	global_load_lds_dwordx4 v210, s[26:27]
	s_mov_b32 m0, s72
	s_nop 0
	global_load_lds_dwordx4 v208, s[26:27]
	s_waitcnt vmcnt(8)
	s_waitcnt lgkmcnt(0)
	s_barrier
	s_setprio 3
	s_waitcnt lgkmcnt(0)
	v_mfma_f32_16x16x32_bf16 v[150:153], v[114:117], v[162:165], v[150:153]
	v_mfma_f32_16x16x32_bf16 v[146:149], v[130:133], v[162:165], v[146:149]
	v_mfma_f32_16x16x32_bf16 v[110:113], v[114:117], v[170:173], v[110:113]
	v_mfma_f32_16x16x32_bf16 v[106:109], v[130:133], v[170:173], v[106:109]
	v_mfma_f32_16x16x32_bf16 v[94:97], v[114:117], v[178:181], v[94:97]
	v_mfma_f32_16x16x32_bf16 v[90:93], v[130:133], v[178:181], v[90:93]
	v_mfma_f32_16x16x32_bf16 v[78:81], v[114:117], v[186:189], v[78:81]
	v_mfma_f32_16x16x32_bf16 v[74:77], v[130:133], v[186:189], v[74:77]
	v_mfma_f32_16x16x32_bf16 v[150:153], v[118:121], v[166:169], v[150:153]
	v_mfma_f32_16x16x32_bf16 v[146:149], v[134:137], v[166:169], v[146:149]
	v_mfma_f32_16x16x32_bf16 v[110:113], v[118:121], v[174:177], v[110:113]
	v_mfma_f32_16x16x32_bf16 v[106:109], v[134:137], v[174:177], v[106:109]
	v_mfma_f32_16x16x32_bf16 v[94:97], v[118:121], v[182:185], v[94:97]
	v_mfma_f32_16x16x32_bf16 v[90:93], v[134:137], v[182:185], v[90:93]
	v_mfma_f32_16x16x32_bf16 v[78:81], v[118:121], v[190:193], v[78:81]
	v_mfma_f32_16x16x32_bf16 v[74:77], v[134:137], v[190:193], v[74:77]
	s_setprio 0
	s_setprio 3
	v_mfma_f32_16x16x32_bf16 v[126:129], v[138:141], v[162:165], v[126:129]
	v_mfma_f32_16x16x32_bf16 v[122:125], v[154:157], v[162:165], v[122:125]
	v_mfma_f32_16x16x32_bf16 v[102:105], v[138:141], v[170:173], v[102:105]
	v_mfma_f32_16x16x32_bf16 v[98:101], v[154:157], v[170:173], v[98:101]
	v_mfma_f32_16x16x32_bf16 v[86:89], v[138:141], v[178:181], v[86:89]
	v_mfma_f32_16x16x32_bf16 v[82:85], v[154:157], v[178:181], v[82:85]
	v_mfma_f32_16x16x32_bf16 v[70:73], v[138:141], v[186:189], v[70:73]
	v_mfma_f32_16x16x32_bf16 v[66:69], v[154:157], v[186:189], v[66:69]
	v_mfma_f32_16x16x32_bf16 v[126:129], v[142:145], v[166:169], v[126:129]
	v_mfma_f32_16x16x32_bf16 v[122:125], v[158:161], v[166:169], v[122:125]
	v_mfma_f32_16x16x32_bf16 v[102:105], v[142:145], v[174:177], v[102:105]
	v_mfma_f32_16x16x32_bf16 v[98:101], v[158:161], v[174:177], v[98:101]
	v_mfma_f32_16x16x32_bf16 v[86:89], v[142:145], v[182:185], v[86:89]
	v_mfma_f32_16x16x32_bf16 v[82:85], v[158:161], v[182:185], v[82:85]
	v_mfma_f32_16x16x32_bf16 v[70:73], v[142:145], v[190:193], v[70:73]
	v_mfma_f32_16x16x32_bf16 v[66:69], v[158:161], v[190:193], v[66:69]
	s_setprio 0
	s_barrier
	s_add_i32 s43, s43, s60
	s_mov_b32 m0, s43
	s_add_u32 s26, s54, 0x80
	s_addc_u32 s27, s55, 0
	ds_read_b128 v[162:165], v245 offset:49152
	ds_read_b128 v[166:169], v245 offset:50176
	ds_read_b128 v[170:173], v245 offset:51200
	ds_read_b128 v[174:177], v245 offset:52224
	ds_read_b128 v[178:181], v245 offset:53248
	ds_read_b128 v[182:185], v245 offset:54272
	ds_read_b128 v[186:189], v245 offset:55296
	ds_read_b128 v[190:193], v245 offset:56320
	global_load_lds_dwordx4 v64, s[26:27]
	s_add_i32 m0, s43, 0x2000
	s_add_i32 s43, s44, s60
	global_load_lds_dwordx4 v206, s[26:27]
	s_add_u32 s26, s26, 0x160000
	s_addc_u32 s27, s27, 0
	s_mov_b32 m0, s43
	s_nop 0
	global_load_lds_dwordx4 v64, s[26:27]
	s_add_i32 m0, s43, 0x2000
	s_nop 0
	global_load_lds_dwordx4 v206, s[26:27]
	s_add_u32 s26, s56, 0x80
	s_addc_u32 s27, s57, 0
	s_mov_b32 m0, s80
	s_nop 0
	global_load_lds_dwordx4 v210, s[26:27]
	s_mov_b32 m0, s81
	s_nop 0
	global_load_lds_dwordx4 v208, s[26:27]
	s_waitcnt vmcnt(8)
	s_waitcnt lgkmcnt(0)
	s_barrier
	s_setprio 3
	s_waitcnt lgkmcnt(0)
	v_mfma_f32_16x16x32_bf16 v[60:63], v[114:117], v[162:165], v[60:63]
	v_mfma_f32_16x16x32_bf16 v[56:59], v[130:133], v[162:165], v[56:59]
	v_mfma_f32_16x16x32_bf16 v[44:47], v[114:117], v[170:173], v[44:47]
	v_mfma_f32_16x16x32_bf16 v[40:43], v[130:133], v[170:173], v[40:43]
	v_mfma_f32_16x16x32_bf16 v[28:31], v[114:117], v[178:181], v[28:31]
	v_mfma_f32_16x16x32_bf16 v[24:27], v[130:133], v[178:181], v[24:27]
	v_mfma_f32_16x16x32_bf16 v[12:15], v[114:117], v[186:189], v[12:15]
	v_mfma_f32_16x16x32_bf16 v[8:11], v[130:133], v[186:189], v[8:11]
	v_mfma_f32_16x16x32_bf16 v[60:63], v[118:121], v[166:169], v[60:63]
	v_mfma_f32_16x16x32_bf16 v[56:59], v[134:137], v[166:169], v[56:59]
	v_mfma_f32_16x16x32_bf16 v[44:47], v[118:121], v[174:177], v[44:47]
	v_mfma_f32_16x16x32_bf16 v[40:43], v[134:137], v[174:177], v[40:43]
	v_mfma_f32_16x16x32_bf16 v[28:31], v[118:121], v[182:185], v[28:31]
	v_mfma_f32_16x16x32_bf16 v[24:27], v[134:137], v[182:185], v[24:27]
	v_mfma_f32_16x16x32_bf16 v[12:15], v[118:121], v[190:193], v[12:15]
	v_mfma_f32_16x16x32_bf16 v[8:11], v[134:137], v[190:193], v[8:11]
	s_setprio 0
	s_setprio 3
	v_mfma_f32_16x16x32_bf16 v[52:55], v[138:141], v[162:165], v[52:55]
	v_mfma_f32_16x16x32_bf16 v[48:51], v[154:157], v[162:165], v[48:51]
	v_mfma_f32_16x16x32_bf16 v[36:39], v[138:141], v[170:173], v[36:39]
	v_mfma_f32_16x16x32_bf16 v[32:35], v[154:157], v[170:173], v[32:35]
	v_mfma_f32_16x16x32_bf16 v[20:23], v[138:141], v[178:181], v[20:23]
	v_mfma_f32_16x16x32_bf16 v[16:19], v[154:157], v[178:181], v[16:19]
	v_mfma_f32_16x16x32_bf16 v[4:7], v[138:141], v[186:189], v[4:7]
	v_mfma_f32_16x16x32_bf16 v[0:3], v[154:157], v[186:189], v[0:3]
	v_mfma_f32_16x16x32_bf16 v[52:55], v[142:145], v[166:169], v[52:55]
	v_mfma_f32_16x16x32_bf16 v[48:51], v[158:161], v[166:169], v[48:51]
	v_mfma_f32_16x16x32_bf16 v[36:39], v[142:145], v[174:177], v[36:39]
	v_mfma_f32_16x16x32_bf16 v[32:35], v[158:161], v[174:177], v[32:35]
	v_mfma_f32_16x16x32_bf16 v[20:23], v[142:145], v[182:185], v[20:23]
	v_mfma_f32_16x16x32_bf16 v[16:19], v[158:161], v[182:185], v[16:19]
	v_mfma_f32_16x16x32_bf16 v[4:7], v[142:145], v[190:193], v[4:7]
	v_mfma_f32_16x16x32_bf16 v[0:3], v[158:161], v[190:193], v[0:3]
	s_setprio 0
	s_barrier
	s_add_i32 vcc_hi, vcc_hi, 2
	s_add_u32 s45, s45, 0x100
	s_addc_u32 vcc_lo, vcc_lo, 0
	s_cmpk_gt_u32 vcc_hi, 0x55
	s_mov_b64 s[26:27], s[22:23]
	s_cbranch_scc0 .LBB0_260
	v_readlane_b32 s22, v255, 6
	v_readlane_b32 s23, v255, 7
	s_and_b64 vcc, exec, s[22:23]
	s_cbranch_vccz .LBB0_263
	s_barrier
